# spatial gating phase: ks loop unrolled; weight fragments loaded up front (counted vmcnt) and 8 LDS fragment reads per trip issued together
# baseline (speedup 1.0000x reference)
.LBB0_263:
	s_and_b32 s18, s23, 0x780
	v_add_u32_e32 v52, s18, v83
	v_lshlrev_b64 v[16:17], 8, v[52:53]
	v_add_u32_e32 v52, s45, v83
	v_lshl_add_u64 v[18:19], v[52:53], 2, s[12:13]
	s_waitcnt lgkmcnt(0)
	s_barrier
	global_load_dword v89, v[18:19], off
	v_lshl_add_u64 v[80:81], v[58:59], 0, v[16:17]
	v_mov_b32_e32 v16, 0
	v_mov_b32_e32 v52, v85
	s_mov_b32 s18, s36
	v_mov_b32_e32 v17, v16
	v_mov_b32_e32 v18, v16
	v_mov_b32_e32 v19, v16
	v_mov_b32_e32 v20, v16
	v_mov_b32_e32 v21, v16
	v_mov_b32_e32 v22, v16
	v_mov_b32_e32 v23, v16
	v_mov_b32_e32 v24, v16
	v_mov_b32_e32 v25, v16
	v_mov_b32_e32 v26, v16
	v_mov_b32_e32 v27, v16
	v_mov_b32_e32 v28, v16
	v_mov_b32_e32 v29, v16
	v_mov_b32_e32 v30, v16
	v_mov_b32_e32 v31, v16
	v_mov_b32_e32 v32, v16
	v_mov_b32_e32 v33, v16
	v_mov_b32_e32 v34, v16
	v_mov_b32_e32 v35, v16
	v_mov_b32_e32 v36, v16
	v_mov_b32_e32 v37, v16
	v_mov_b32_e32 v38, v16
	v_mov_b32_e32 v39, v16
	v_mov_b32_e32 v40, v16
	v_mov_b32_e32 v41, v16
	v_mov_b32_e32 v42, v16
	v_mov_b32_e32 v43, v16
	v_mov_b32_e32 v44, v16
	v_mov_b32_e32 v45, v16
	v_mov_b32_e32 v46, v16
	v_mov_b32_e32 v47, v16
	global_load_dwordx4 v[122:125], v[80:81], off
	global_load_dwordx4 v[126:129], v[80:81], off offset:64
	global_load_dwordx4 v[130:133], v[80:81], off offset:128
	global_load_dwordx4 v[134:137], v[80:81], off offset:192
	ds_read_b128 v[138:141], v52
	ds_read_b128 v[142:145], v52 offset:4352
	ds_read_b128 v[146:149], v52 offset:8704
	ds_read_b128 v[150:153], v52 offset:13056
	ds_read_b128 v[154:157], v52 offset:17408
	ds_read_b128 v[158:161], v52 offset:21760
	ds_read_b128 v[162:165], v52 offset:26112
	ds_read_b128 v[166:169], v52 offset:30464
	s_waitcnt vmcnt(3)
	s_waitcnt lgkmcnt(7)
	v_mfma_f32_16x16x32_bf16 v[44:47], v[138:141], v[122:125], v[44:47]
	s_waitcnt lgkmcnt(6)
	v_mfma_f32_16x16x32_bf16 v[40:43], v[142:145], v[122:125], v[40:43]
	s_waitcnt lgkmcnt(5)
	v_mfma_f32_16x16x32_bf16 v[36:39], v[146:149], v[122:125], v[36:39]
	s_waitcnt lgkmcnt(4)
	v_mfma_f32_16x16x32_bf16 v[32:35], v[150:153], v[122:125], v[32:35]
	s_waitcnt lgkmcnt(3)
	v_mfma_f32_16x16x32_bf16 v[28:31], v[154:157], v[122:125], v[28:31]
	s_waitcnt lgkmcnt(2)
	v_mfma_f32_16x16x32_bf16 v[24:27], v[158:161], v[122:125], v[24:27]
	s_waitcnt lgkmcnt(1)
	v_mfma_f32_16x16x32_bf16 v[20:23], v[162:165], v[122:125], v[20:23]
	s_waitcnt lgkmcnt(0)
	v_mfma_f32_16x16x32_bf16 v[16:19], v[166:169], v[122:125], v[16:19]
	s_add_i32 s18, s18, -1
	s_cmp_eq_u32 s18, 0
	s_cbranch_scc1 .Lspat_ks_done
	ds_read_b128 v[138:141], v52 offset:64
	ds_read_b128 v[142:145], v52 offset:4416
	ds_read_b128 v[146:149], v52 offset:8768
	ds_read_b128 v[150:153], v52 offset:13120
	ds_read_b128 v[154:157], v52 offset:17472
	ds_read_b128 v[158:161], v52 offset:21824
	ds_read_b128 v[162:165], v52 offset:26176
	ds_read_b128 v[166:169], v52 offset:30528
	s_waitcnt vmcnt(2)
	s_waitcnt lgkmcnt(7)
	v_mfma_f32_16x16x32_bf16 v[44:47], v[138:141], v[126:129], v[44:47]
	s_waitcnt lgkmcnt(6)
	v_mfma_f32_16x16x32_bf16 v[40:43], v[142:145], v[126:129], v[40:43]
	s_waitcnt lgkmcnt(5)
	v_mfma_f32_16x16x32_bf16 v[36:39], v[146:149], v[126:129], v[36:39]
	s_waitcnt lgkmcnt(4)
	v_mfma_f32_16x16x32_bf16 v[32:35], v[150:153], v[126:129], v[32:35]
	s_waitcnt lgkmcnt(3)
	v_mfma_f32_16x16x32_bf16 v[28:31], v[154:157], v[126:129], v[28:31]
	s_waitcnt lgkmcnt(2)
	v_mfma_f32_16x16x32_bf16 v[24:27], v[158:161], v[126:129], v[24:27]
	s_waitcnt lgkmcnt(1)
	v_mfma_f32_16x16x32_bf16 v[20:23], v[162:165], v[126:129], v[20:23]
	s_waitcnt lgkmcnt(0)
	v_mfma_f32_16x16x32_bf16 v[16:19], v[166:169], v[126:129], v[16:19]
	s_add_i32 s18, s18, -1
	s_cmp_eq_u32 s18, 0
	s_cbranch_scc1 .Lspat_ks_done
	ds_read_b128 v[138:141], v52 offset:128
	ds_read_b128 v[142:145], v52 offset:4480
	ds_read_b128 v[146:149], v52 offset:8832
	ds_read_b128 v[150:153], v52 offset:13184
	ds_read_b128 v[154:157], v52 offset:17536
	ds_read_b128 v[158:161], v52 offset:21888
	ds_read_b128 v[162:165], v52 offset:26240
	ds_read_b128 v[166:169], v52 offset:30592
	s_waitcnt vmcnt(1)
	s_waitcnt lgkmcnt(7)
	v_mfma_f32_16x16x32_bf16 v[44:47], v[138:141], v[130:133], v[44:47]
	s_waitcnt lgkmcnt(6)
	v_mfma_f32_16x16x32_bf16 v[40:43], v[142:145], v[130:133], v[40:43]
	s_waitcnt lgkmcnt(5)
	v_mfma_f32_16x16x32_bf16 v[36:39], v[146:149], v[130:133], v[36:39]
	s_waitcnt lgkmcnt(4)
	v_mfma_f32_16x16x32_bf16 v[32:35], v[150:153], v[130:133], v[32:35]
	s_waitcnt lgkmcnt(3)
	v_mfma_f32_16x16x32_bf16 v[28:31], v[154:157], v[130:133], v[28:31]
	s_waitcnt lgkmcnt(2)
	v_mfma_f32_16x16x32_bf16 v[24:27], v[158:161], v[130:133], v[24:27]
	s_waitcnt lgkmcnt(1)
	v_mfma_f32_16x16x32_bf16 v[20:23], v[162:165], v[130:133], v[20:23]
	s_waitcnt lgkmcnt(0)
	v_mfma_f32_16x16x32_bf16 v[16:19], v[166:169], v[130:133], v[16:19]
	s_add_i32 s18, s18, -1
	s_cmp_eq_u32 s18, 0
	s_cbranch_scc1 .Lspat_ks_done
	ds_read_b128 v[138:141], v52 offset:192
	ds_read_b128 v[142:145], v52 offset:4544
	ds_read_b128 v[146:149], v52 offset:8896
	ds_read_b128 v[150:153], v52 offset:13248
	ds_read_b128 v[154:157], v52 offset:17600
	ds_read_b128 v[158:161], v52 offset:21952
	ds_read_b128 v[162:165], v52 offset:26304
	ds_read_b128 v[166:169], v52 offset:30656
	s_waitcnt vmcnt(0)
	s_waitcnt lgkmcnt(7)
	v_mfma_f32_16x16x32_bf16 v[44:47], v[138:141], v[134:137], v[44:47]
	s_waitcnt lgkmcnt(6)
	v_mfma_f32_16x16x32_bf16 v[40:43], v[142:145], v[134:137], v[40:43]
	s_waitcnt lgkmcnt(5)
	v_mfma_f32_16x16x32_bf16 v[36:39], v[146:149], v[134:137], v[36:39]
	s_waitcnt lgkmcnt(4)
	v_mfma_f32_16x16x32_bf16 v[32:35], v[150:153], v[134:137], v[32:35]
	s_waitcnt lgkmcnt(3)
	v_mfma_f32_16x16x32_bf16 v[28:31], v[154:157], v[134:137], v[28:31]
	s_waitcnt lgkmcnt(2)
	v_mfma_f32_16x16x32_bf16 v[24:27], v[158:161], v[134:137], v[24:27]
	s_waitcnt lgkmcnt(1)
	v_mfma_f32_16x16x32_bf16 v[20:23], v[162:165], v[134:137], v[20:23]
	s_waitcnt lgkmcnt(0)
	v_mfma_f32_16x16x32_bf16 v[16:19], v[166:169], v[134:137], v[16:19]
.Lspat_ks_done:
	v_lshlrev_b32_e32 v80, 16, v78
	v_add_f32_e32 v44, v89, v44
	v_and_b32_e32 v78, 0xffff0000, v78
	v_add_f32_e32 v45, v89, v45
	v_mul_f32_e32 v44, v44, v80
	v_mul_f32_e32 v45, v45, v78
	v_cvt_pk_bf16_f32 v44, v44, v45
	v_lshlrev_b32_e32 v45, 16, v79
	v_add_f32_e32 v46, v89, v46
	v_or_b32_e32 v52, s45, v50
	v_lshlrev_b64 v[76:77], 12, v[76:77]
	v_mul_f32_e32 v45, v46, v45
	v_and_b32_e32 v46, 0xffff0000, v79
	v_add_f32_e32 v47, v89, v47
	v_lshl_add_u64 v[76:77], s[14:15], 0, v[76:77]
	v_mul_f32_e32 v46, v47, v46
	v_lshlrev_b32_e32 v52, 1, v52
	v_cvt_pk_bf16_f32 v45, v45, v46
	v_lshl_add_u64 v[46:47], v[76:77], 0, v[52:53]
	global_store_dwordx2 v[46:47], v[44:45], off
	v_lshlrev_b32_e32 v44, 16, v74
	v_add_f32_e32 v40, v89, v40
	v_mul_f32_e32 v40, v40, v44
	v_and_b32_e32 v44, 0xffff0000, v74
	v_add_f32_e32 v41, v89, v41
	v_mul_f32_e32 v41, v41, v44
	v_cvt_pk_bf16_f32 v40, v40, v41
	v_lshlrev_b32_e32 v41, 16, v75
	v_add_f32_e32 v42, v89, v42
	v_mul_f32_e32 v41, v42, v41
	v_and_b32_e32 v42, 0xffff0000, v75
	v_add_f32_e32 v43, v89, v43
	v_mul_f32_e32 v42, v43, v42
	v_cvt_pk_bf16_f32 v41, v41, v42
	global_store_dwordx2 v[46:47], v[40:41], off offset:32
	v_lshlrev_b32_e32 v40, 16, v72
	v_add_f32_e32 v36, v89, v36
	v_mul_f32_e32 v36, v36, v40
	v_and_b32_e32 v40, 0xffff0000, v72
	v_add_f32_e32 v37, v89, v37
	v_mul_f32_e32 v37, v37, v40
	v_cvt_pk_bf16_f32 v36, v36, v37
	v_lshlrev_b32_e32 v37, 16, v73
	v_add_f32_e32 v38, v89, v38
	v_mul_f32_e32 v37, v38, v37
	v_and_b32_e32 v38, 0xffff0000, v73
	v_add_f32_e32 v39, v89, v39
	v_mul_f32_e32 v38, v39, v38
	v_cvt_pk_bf16_f32 v37, v37, v38
	global_store_dwordx2 v[46:47], v[36:37], off offset:64
	v_lshlrev_b32_e32 v36, 16, v70
	v_add_f32_e32 v32, v89, v32
	v_mul_f32_e32 v32, v32, v36
	v_and_b32_e32 v36, 0xffff0000, v70
	v_add_f32_e32 v33, v89, v33
	v_mul_f32_e32 v33, v33, v36
	v_cvt_pk_bf16_f32 v32, v32, v33
	v_lshlrev_b32_e32 v33, 16, v71
	v_add_f32_e32 v34, v89, v34
	v_mul_f32_e32 v33, v34, v33
	v_and_b32_e32 v34, 0xffff0000, v71
	v_add_f32_e32 v35, v89, v35
	v_mul_f32_e32 v34, v35, v34
	v_cvt_pk_bf16_f32 v33, v33, v34
	global_store_dwordx2 v[46:47], v[32:33], off offset:96
	v_lshlrev_b32_e32 v32, 16, v68
	v_add_f32_e32 v28, v89, v28
	v_mul_f32_e32 v28, v28, v32
	v_and_b32_e32 v32, 0xffff0000, v68
	v_add_f32_e32 v29, v89, v29
	v_mul_f32_e32 v29, v29, v32
	v_cvt_pk_bf16_f32 v28, v28, v29
	v_lshlrev_b32_e32 v29, 16, v69
	v_add_f32_e32 v30, v89, v30
	v_mul_f32_e32 v29, v30, v29
	v_and_b32_e32 v30, 0xffff0000, v69
	v_add_f32_e32 v31, v89, v31
	v_mul_f32_e32 v30, v31, v30
	v_cvt_pk_bf16_f32 v29, v29, v30
	global_store_dwordx2 v[46:47], v[28:29], off offset:128
	v_lshlrev_b32_e32 v28, 16, v66
	v_add_f32_e32 v24, v89, v24
	v_mul_f32_e32 v24, v24, v28
	v_and_b32_e32 v28, 0xffff0000, v66
	v_add_f32_e32 v25, v89, v25
	v_mul_f32_e32 v25, v25, v28
	v_cvt_pk_bf16_f32 v24, v24, v25
	v_lshlrev_b32_e32 v25, 16, v67
	v_add_f32_e32 v26, v89, v26
	v_mul_f32_e32 v25, v26, v25
	v_and_b32_e32 v26, 0xffff0000, v67
	v_add_f32_e32 v27, v89, v27
	v_mul_f32_e32 v26, v27, v26
	v_cvt_pk_bf16_f32 v25, v25, v26
	global_store_dwordx2 v[46:47], v[24:25], off offset:160
	v_lshlrev_b32_e32 v24, 16, v64
	v_add_f32_e32 v20, v89, v20
	v_mul_f32_e32 v20, v20, v24
	v_and_b32_e32 v24, 0xffff0000, v64
	v_add_f32_e32 v21, v89, v21
	v_mul_f32_e32 v21, v21, v24
	v_cvt_pk_bf16_f32 v20, v20, v21
	v_lshlrev_b32_e32 v21, 16, v65
	v_add_f32_e32 v22, v89, v22
	v_mul_f32_e32 v21, v22, v21
	v_and_b32_e32 v22, 0xffff0000, v65
	v_add_f32_e32 v23, v89, v23
	v_mul_f32_e32 v22, v23, v22
	v_cvt_pk_bf16_f32 v21, v21, v22
	global_store_dwordx2 v[46:47], v[20:21], off offset:192
	v_lshlrev_b32_e32 v20, 16, v62
	v_add_f32_e32 v16, v89, v16
	v_mul_f32_e32 v16, v16, v20
	v_and_b32_e32 v20, 0xffff0000, v62
	v_add_f32_e32 v17, v89, v17
	v_mul_f32_e32 v17, v17, v20
	v_cvt_pk_bf16_f32 v16, v16, v17
	v_lshlrev_b32_e32 v17, 16, v63
	v_add_f32_e32 v18, v89, v18
	v_mul_f32_e32 v17, v18, v17
	v_and_b32_e32 v18, 0xffff0000, v63
	v_add_f32_e32 v19, v89, v19
	s_add_i32 s23, s23, s37
	s_and_b64 vcc, exec, s[26:27]
	v_mul_f32_e32 v18, v19, v18
	v_cvt_pk_bf16_f32 v17, v17, v18
	global_store_dwordx2 v[46:47], v[16:17], off offset:224
	s_cbranch_vccz .LBB0_259
